# k33_sleep4
# speedup vs baseline: 1.0111x; 1.0111x over previous
; #define PH_SYNC(n) run_phase<n>(p, smem); grid.sync();
; __global__ void __launch_bounds__(256, 2) hybrid_fwd(Params p) {
;   __shared__ __attribute__((aligned(16))) char smem[SMEM_BYTES];
;   cg::grid_group grid = cg::this_grid();
;   PH_SYNC(0) PH_SYNC(1) PH_SYNC(2) PH_SYNC(3) PH_SYNC(4) PH_SYNC(5) PH_SYNC(6) PH_SYNC(7)
;   PH_SYNC(8) PH_SYNC(17) PH_SYNC(9) PH_SYNC(10) PH_SYNC(11) PH_SYNC(12) PH_SYNC(13) PH_SYNC(14) PH_SYNC(15)
;   PH_SYNC(16)
.Lmy_gs_poll_1:
	s_sleep 4
	global_load_dword v0, v2, s[10:11] sc1
	s_add_u32 s13, s13, 1
	s_waitcnt vmcnt(0)
	v_cmp_ge_u32_e32 vcc, v0, v1
	s_cmp_lg_u64 vcc, 0
	s_cbranch_scc1 .Lmy_gs_done_1
	s_cmp_lt_u32 s13, 0x40000
	s_cbranch_scc1 .Lmy_gs_poll_1

; #define PH_SYNC(n) run_phase<n>(p, smem); grid.sync();
; __global__ void __launch_bounds__(256, 2) hybrid_fwd(Params p) {
;   __shared__ __attribute__((aligned(16))) char smem[SMEM_BYTES];
;   cg::grid_group grid = cg::this_grid();
;   PH_SYNC(0) PH_SYNC(1) PH_SYNC(2) PH_SYNC(3) PH_SYNC(4) PH_SYNC(5) PH_SYNC(6) PH_SYNC(7)
;   PH_SYNC(8) PH_SYNC(17) PH_SYNC(9) PH_SYNC(10) PH_SYNC(11) PH_SYNC(12) PH_SYNC(13) PH_SYNC(14) PH_SYNC(15)
;   PH_SYNC(16)
.Lmy_gs_poll_3:
	s_sleep 4
	global_load_dword v0, v2, s[8:9] sc1
	s_add_u32 s11, s11, 1
	s_waitcnt vmcnt(0)
	v_cmp_ge_u32_e32 vcc, v0, v1
	s_cmp_lg_u64 vcc, 0
	s_cbranch_scc1 .Lmy_gs_done_3
	s_cmp_lt_u32 s11, 0x40000
	s_cbranch_scc1 .Lmy_gs_poll_3

; #define PH_SYNC(n) run_phase<n>(p, smem); grid.sync();
; __global__ void __launch_bounds__(256, 2) hybrid_fwd(Params p) {
;   __shared__ __attribute__((aligned(16))) char smem[SMEM_BYTES];
;   cg::grid_group grid = cg::this_grid();
;   PH_SYNC(0) PH_SYNC(1) PH_SYNC(2) PH_SYNC(3) PH_SYNC(4) PH_SYNC(5) PH_SYNC(6) PH_SYNC(7)
;   PH_SYNC(8) PH_SYNC(17) PH_SYNC(9) PH_SYNC(10) PH_SYNC(11) PH_SYNC(12) PH_SYNC(13) PH_SYNC(14) PH_SYNC(15)
;   PH_SYNC(16)
.Lmy_gs_poll_5:
	s_sleep 4
	global_load_dword v0, v2, s[12:13] sc1
	s_add_u32 s15, s15, 1
	s_waitcnt vmcnt(0)
	v_cmp_ge_u32_e32 vcc, v0, v1
	s_cmp_lg_u64 vcc, 0
	s_cbranch_scc1 .Lmy_gs_done_5
	s_cmp_lt_u32 s15, 0x40000
	s_cbranch_scc1 .Lmy_gs_poll_5

; #define PH_SYNC(n) run_phase<n>(p, smem); grid.sync();
; __global__ void __launch_bounds__(256, 2) hybrid_fwd(Params p) {
;   __shared__ __attribute__((aligned(16))) char smem[SMEM_BYTES];
;   cg::grid_group grid = cg::this_grid();
;   PH_SYNC(0) PH_SYNC(1) PH_SYNC(2) PH_SYNC(3) PH_SYNC(4) PH_SYNC(5) PH_SYNC(6) PH_SYNC(7)
;   PH_SYNC(8) PH_SYNC(17) PH_SYNC(9) PH_SYNC(10) PH_SYNC(11) PH_SYNC(12) PH_SYNC(13) PH_SYNC(14) PH_SYNC(15)
;   PH_SYNC(16)
.Lsy0_poll:
	s_sleep 4
	global_load_dword v0, v2, s[26:27] sc1
	s_add_u32 s25, s25, 1
	s_waitcnt vmcnt(0)
	v_cmp_ge_u32_e32 vcc, v0, v1
	s_cmp_lg_u64 vcc, 0
	s_cbranch_scc1 .Lsy0_done
	s_cmp_lt_u32 s25, 0x40000
	s_cbranch_scc1 .Lsy0_poll

; #define PH_SYNC(n) run_phase<n>(p, smem); grid.sync();
; __global__ void __launch_bounds__(256, 2) hybrid_fwd(Params p) {
;   __shared__ __attribute__((aligned(16))) char smem[SMEM_BYTES];
;   cg::grid_group grid = cg::this_grid();
;   PH_SYNC(0) PH_SYNC(1) PH_SYNC(2) PH_SYNC(3) PH_SYNC(4) PH_SYNC(5) PH_SYNC(6) PH_SYNC(7)
;   PH_SYNC(8) PH_SYNC(17) PH_SYNC(9) PH_SYNC(10) PH_SYNC(11) PH_SYNC(12) PH_SYNC(13) PH_SYNC(14) PH_SYNC(15)
;   PH_SYNC(16)
.Lmy_gs_poll_9:
	s_sleep 4
	global_load_dword v0, v2, s[14:15] sc1
	s_add_u32 s17, s17, 1
	s_waitcnt vmcnt(0)
	v_cmp_ge_u32_e32 vcc, v0, v1
	s_cmp_lg_u64 vcc, 0
	s_cbranch_scc1 .Lmy_gs_done_9
	s_cmp_lt_u32 s17, 0x40000
	s_cbranch_scc1 .Lmy_gs_poll_9

; #define PH_SYNC(n) run_phase<n>(p, smem); grid.sync();
; __global__ void __launch_bounds__(256, 2) hybrid_fwd(Params p) {
;   __shared__ __attribute__((aligned(16))) char smem[SMEM_BYTES];
;   cg::grid_group grid = cg::this_grid();
;   PH_SYNC(0) PH_SYNC(1) PH_SYNC(2) PH_SYNC(3) PH_SYNC(4) PH_SYNC(5) PH_SYNC(6) PH_SYNC(7)
;   PH_SYNC(8) PH_SYNC(17) PH_SYNC(9) PH_SYNC(10) PH_SYNC(11) PH_SYNC(12) PH_SYNC(13) PH_SYNC(14) PH_SYNC(15)
;   PH_SYNC(16)
.Lmy_gs_poll_16:
	s_sleep 4
	global_load_dword v0, v2, s[6:7] sc1
	s_add_u32 s9, s9, 1
	s_waitcnt vmcnt(0)
	v_cmp_ge_u32_e32 vcc, v0, v1
	s_cmp_lg_u64 vcc, 0
	s_cbranch_scc1 .Lmy_gs_done_16
	s_cmp_lt_u32 s9, 0x40000
	s_cbranch_scc1 .Lmy_gs_poll_16

; #define PH_SYNC(n) run_phase<n>(p, smem); grid.sync();
; __global__ void __launch_bounds__(256, 2) hybrid_fwd(Params p) {
;   __shared__ __attribute__((aligned(16))) char smem[SMEM_BYTES];
;   cg::grid_group grid = cg::this_grid();
;   PH_SYNC(0) PH_SYNC(1) PH_SYNC(2) PH_SYNC(3) PH_SYNC(4) PH_SYNC(5) PH_SYNC(6) PH_SYNC(7)
;   PH_SYNC(8) PH_SYNC(17) PH_SYNC(9) PH_SYNC(10) PH_SYNC(11) PH_SYNC(12) PH_SYNC(13) PH_SYNC(14) PH_SYNC(15)
;   PH_SYNC(16)
.Lmy_gs_poll_17:
	s_sleep 4
	global_load_dword v0, v2, s[0:1] sc1
	s_add_u32 s5, s5, 1
	s_waitcnt vmcnt(0)
	v_cmp_ge_u32_e32 vcc, v0, v1
	s_cmp_lg_u64 vcc, 0
	s_cbranch_scc1 .Lmy_gs_done_17
	s_cmp_lt_u32 s5, 0x40000
	s_cbranch_scc1 .Lmy_gs_poll_17
